# slab-local barrier before P10: 20th-of-32 arriver flushes its L2 early so the kernel ends with a clean L2 (on top of write-through P10 stores)
# baseline (speedup 1.0000x reference)
; __device__ __forceinline__ unsigned xb_ld(unsigned* p)              { return __hip_atomic_load(p, __ATOMIC_RELAXED, __HIP_MEMORY_SCOPE_AGENT); }
; __device__ __forceinline__ unsigned xb_add(unsigned* p, unsigned v) { return __hip_atomic_fetch_add(p, v, __ATOMIC_RELAXED, __HIP_MEMORY_SCOPE_AGENT); }
; __device__ __forceinline__ void xcd_barrier_complete(unsigned* bar, unsigned x, unsigned& nloc, unsigned& nx) {
;     ...
;         for (unsigned j = 0; j < 16; ++j) { const unsigned c = xb_ld(&bar[XB_XCNT(j)]); sum += c; cnt += (c > 0u) ? 1u : 0u; mine = (j == x) ? c : mine; }
;         if (sum == G) break;
;         __builtin_amdgcn_s_sleep(1);
;         if ((++sp & 255u) == 0u) { if (xb_ld(&bar[XB_TMO])) break; if (sp > XB_SPIN_CAP) { atomicAdd(&bar[XB_TMO], 1u); break; } }
;     }
;     nloc = mine > 0u ? mine : 1u; nx = cnt > 0u ? cnt : 1u;
; }
; __device__ __forceinline__ void xcd_barrier(const XcdBarrier& b) {
;     asm volatile("s_waitcnt vmcnt(0)" ::: "memory");
;     __syncthreads();
;     if (threadIdx.x == 0) {
;         unsigned* bar = b.bar;
;         __builtin_amdgcn_s_waitcnt(0);
;         unsigned nloc = b.st[0], nx = b.st[1];
;         if (nloc == 0u) { xcd_barrier_complete(bar, b.x, nloc, nx); b.st[0] = nloc; b.st[1] = nx; }
;         const unsigned old = xb_add(&bar[XB_XSUB(b.x)], 1u);
;         const unsigned gen = old / nloc;
;         if (old + 1u == (gen + 1u) * nloc) {
.LBB0_968:
	v_readlane_b32 s2, v241, 62
	v_readlane_b32 s3, v241, 63
	v_cmp_ne_u32_e32 vcc, 0, v0
	s_nop 0
	v_cndmask_b32_e64 v16, 0, v0, s[2:3]
	v_readlane_b32 s2, v241, 60
	v_readlane_b32 s3, v241, 61
	v_cndmask_b32_e64 v0, 0, 1, vcc
	v_cmp_ne_u32_e32 vcc, 0, v1
	v_cndmask_b32_e64 v16, v16, v1, s[2:3]
	v_readlane_b32 s2, v241, 58
	v_readlane_b32 s3, v241, 59
	v_addc_co_u32_e32 v0, vcc, 0, v0, vcc
	s_nop 0
	v_cndmask_b32_e64 v16, v16, v2, s[2:3]
	v_readlane_b32 s2, v241, 56
	v_readlane_b32 s3, v241, 57
	v_cmp_ne_u32_e32 vcc, 0, v2
	s_nop 0
	v_cndmask_b32_e64 v16, v16, v3, s[2:3]
	v_readlane_b32 s2, v241, 54
	v_readlane_b32 s3, v241, 55
	v_cndmask_b32_e64 v1, 0, 1, vcc
	v_cmp_ne_u32_e32 vcc, 0, v3
	v_cndmask_b32_e64 v16, v16, v4, s[2:3]
	v_readlane_b32 s2, v241, 52
	v_readlane_b32 s3, v241, 53
	v_addc_co_u32_e32 v0, vcc, v0, v1, vcc
	s_nop 0
	v_cndmask_b32_e64 v16, v16, v5, s[2:3]
	v_readlane_b32 s2, v241, 50
	v_readlane_b32 s3, v241, 51
	v_cmp_ne_u32_e32 vcc, 0, v4
	s_nop 0
	v_cndmask_b32_e64 v16, v16, v6, s[2:3]
	v_readlane_b32 s2, v241, 48
	v_readlane_b32 s3, v241, 49
	v_cndmask_b32_e64 v1, 0, 1, vcc
	v_cmp_ne_u32_e32 vcc, 0, v5
	v_cndmask_b32_e64 v16, v16, v7, s[2:3]
	v_readlane_b32 s2, v241, 46
	v_readlane_b32 s3, v241, 47
	v_addc_co_u32_e32 v0, vcc, v0, v1, vcc
	s_nop 0
	v_cndmask_b32_e64 v16, v16, v8, s[2:3]
	v_readlane_b32 s2, v241, 44
	v_readlane_b32 s3, v241, 45
	v_cmp_ne_u32_e32 vcc, 0, v6
	s_nop 0
	v_cndmask_b32_e64 v16, v16, v9, s[2:3]
	v_readlane_b32 s2, v241, 42
	v_cndmask_b32_e64 v1, 0, 1, vcc
	v_cmp_ne_u32_e32 vcc, 0, v7
	v_readlane_b32 s3, v241, 43
	s_nop 0
	v_addc_co_u32_e32 v0, vcc, v0, v1, vcc
	v_cndmask_b32_e64 v16, v16, v10, s[2:3]
	v_readlane_b32 s2, v241, 40
	v_cmp_ne_u32_e32 vcc, 0, v8
	v_readlane_b32 s3, v241, 41
	s_nop 0
	v_cndmask_b32_e64 v1, 0, 1, vcc
	v_cmp_ne_u32_e32 vcc, 0, v9
	v_cndmask_b32_e64 v16, v16, v11, s[2:3]
	v_readlane_b32 s2, v241, 38
	v_addc_co_u32_e32 v0, vcc, v0, v1, vcc
	v_readlane_b32 s3, v241, 39
	v_cmp_ne_u32_e32 vcc, 0, v10
	s_nop 0
	v_cndmask_b32_e64 v16, v16, v12, s[2:3]
	v_readlane_b32 s2, v241, 36
	v_cndmask_b32_e64 v1, 0, 1, vcc
	v_cmp_ne_u32_e32 vcc, 0, v11
	v_readlane_b32 s3, v241, 37
	s_nop 0
	v_addc_co_u32_e32 v0, vcc, v0, v1, vcc
	v_cndmask_b32_e64 v16, v16, v13, s[2:3]
	v_readlane_b32 s2, v241, 34
	v_cmp_ne_u32_e32 vcc, 0, v12
	v_readlane_b32 s3, v241, 35
	s_nop 0
	v_cndmask_b32_e64 v1, 0, 1, vcc
	v_cmp_ne_u32_e32 vcc, 0, v13
	v_cndmask_b32_e64 v16, v16, v14, s[2:3]
	v_readlane_b32 s2, v241, 32
	v_addc_co_u32_e32 v0, vcc, v0, v1, vcc
	v_readlane_b32 s3, v241, 33
	v_cmp_ne_u32_e32 vcc, 0, v14
	s_nop 0
	v_cndmask_b32_e64 v16, v16, v15, s[2:3]
	v_cndmask_b32_e64 v1, 0, 1, vcc
	v_cmp_ne_u32_e32 vcc, 0, v15
	s_add_i32 s2, 0, 0x20160
	v_max_u32_e32 v2, 1, v16
	v_addc_co_u32_e32 v0, vcc, v0, v1, vcc
	v_mov_b32_e32 v1, s2
	s_add_i32 s2, 0, 0x20164
	v_max_u32_e32 v0, 1, v0
	ds_write_b32 v1, v2
	v_mov_b32_e32 v1, s2
	ds_write_b32 v1, v0
.LBB0_969:
	s_cmp_eq_u32 s99, 0
	s_cbranch_scc1 .Lgbar_glob_10
	s_add_i32 s101, s101, 1
	s_add_u32 s4, s58, s98
	s_addc_u32 s5, s59, 0
	v_mov_b32_e32 v3, 1
	v_mov_b32_e32 v4, 0
	global_atomic_add v5, v4, v3, s[4:5] sc0
	v_mov_b32_e32 v6, s101
	v_lshlrev_b32_e32 v6, 5, v6
	s_nop 0
	global_load_dword v3, v4, s[4:5] sc1
	s_waitcnt vmcnt(0)
	v_add_u32_e32 v5, 13, v5
	v_cmp_ne_u32_e32 vcc, v5, v6
	v_mov_b32_e32 v5, 0
	s_cbranch_vccnz .Lgbar_lchk_10
	buffer_wbl2 sc1
	s_waitcnt vmcnt(0)
	s_branch .Lgbar_lloop_10
